# ret gate (phase 10): each 1 KiB quarter of a token row read and written lane-contiguously (was 64B-strided 16B pieces); per-head norm by wave-wide sums
# speedup vs baseline: 1.0108x; 1.0105x over previous
; DI float bflo(unsigned u) { return __uint_as_float(u << 16); }
; DI float bfhi(unsigned u) { return __uint_as_float(u & 0xffff0000u); }
; DI void phase_ret_gate(const Params& p) {
;     const int lane = threadIdx.x & 63, gw = blockIdx.x * 8 + (threadIdx.x >> 6), nw = gridDim.x * 8;
;     const bf16_t* oraw = (const bf16_t*)(p.ws + WS_ORAW); const bf16_t* P1 = (const bf16_t*)(p.ws + WS_P1); bf16_t* og = (bf16_t*)(p.ws + WS_OG);
;     for (int tok = gw; tok < T_TOK; tok += nw) {
;         float o[32]; float ss = 0.f;
; #pragma unroll
;         for (int q = 0; q < 4; ++q) { const u32x4 a = *(const u32x4*)(oraw + (size_t)tok * 2048 + 32 * lane + 8 * q); const unsigned au[4] = {a.x, a.y, a.z, a.w};
; #pragma unroll
;             for (int i = 0; i < 4; ++i) { o[8 * q + 2 * i] = bflo(au[i]); o[8 * q + 2 * i + 1] = bfhi(au[i]); ss += o[8 * q + 2 * i] * o[8 * q + 2 * i] + o[8 * q + 2 * i + 1] * o[8 * q + 2 * i + 1]; } }
;         ss = row16_sum(ss);
;         const float rstd = rsqrtf(ss * (1.f / 512.f) + 1e-6f);
;         const float* wn = p.onorm_b + 32 * lane;
; #pragma unroll
;         for (int q = 0; q < 4; ++q) { const u32x4 g = *(const u32x4*)(P1 + (size_t)tok * LDP1 + 4096 + 32 * lane + 8 * q); const unsigned gu[4] = {g.x, g.y, g.z, g.w}; unsigned r[4];
.LBB0_1446:
	s_cmp_lt_i32 s80, 11
	s_cselect_b64 s[4:5], -1, 0
	s_and_b64 s[0:1], s[4:5], s[0:1]
	s_and_b64 s[0:1], s[44:45], s[0:1]
	s_and_saveexec_b64 s[6:7], s[0:1]
	s_cbranch_execz .LBB0_1449
	v_readlane_b32 s14, v238, 12
	v_readlane_b32 s15, v238, 13
	v_lshlrev_b32_e32 v2, 4, v196
	v_lshlrev_b32_e32 v3, 5, v196
	v_add_u32_e32 v6, 0x1000, v3
	s_add_u32 s10, s78, 0x3c80000
	s_addc_u32 s11, s79, 0
	s_add_u32 s12, s78, 0x1d482000
	s_addc_u32 s13, s79, 0
	s_add_u32 s16, s78, 0x8080000
	s_addc_u32 s17, s79, 0
	global_load_dwordx4 v[16:19], v3, s[14:15]
	global_load_dwordx4 v[20:23], v3, s[14:15] offset:16
	global_load_dwordx4 v[24:27], v3, s[14:15] offset:2048
	global_load_dwordx4 v[28:31], v3, s[14:15] offset:2064
	global_load_dwordx4 v[32:35], v6, s[14:15]
	global_load_dwordx4 v[36:39], v6, s[14:15] offset:16
	global_load_dwordx4 v[40:43], v6, s[14:15] offset:2048
	global_load_dwordx4 v[44:47], v6, s[14:15] offset:2064
	v_readfirstlane_b32 s8, v162
	s_mov_b32 s23, 0
	v_mov_b32_e32 v15, 0x358637bd
	s_lshl_b32 s9, s8, 12
	v_add_u32_e32 v4, s9, v2
	s_mul_i32 s9, s8, 0x3000
	v_add_u32_e32 v5, s9, v2
	global_load_dwordx4 v[48:51], v4, s[10:11]
	global_load_dwordx4 v[52:55], v4, s[10:11] offset:1024
	global_load_dwordx4 v[56:59], v4, s[10:11] offset:2048
	global_load_dwordx4 v[60:63], v4, s[10:11] offset:3072
	global_load_dwordx4 v[64:67], v5, s[12:13]
	global_load_dwordx4 v[68:71], v5, s[12:13] offset:1024
	global_load_dwordx4 v[72:75], v5, s[12:13] offset:2048
	global_load_dwordx4 v[76:79], v5, s[12:13] offset:3072
.Lg10_a:
	s_add_u32 s22, s8, s46
	s_cmp_lt_u32 s22, 0x4400
	s_cbranch_scc0 .Lg10_a_nonext
	s_lshl_b32 s9, s22, 12
	v_add_u32_e32 v4, s9, v2
	s_mul_i32 s9, s22, 0x3000
	v_add_u32_e32 v5, s9, v2
	global_load_dwordx4 v[80:83], v4, s[10:11]
	global_load_dwordx4 v[84:87], v4, s[10:11] offset:1024
	global_load_dwordx4 v[88:91], v4, s[10:11] offset:2048
	global_load_dwordx4 v[92:95], v4, s[10:11] offset:3072
	global_load_dwordx4 v[96:99], v5, s[12:13]
	global_load_dwordx4 v[100:103], v5, s[12:13] offset:1024
	global_load_dwordx4 v[104:107], v5, s[12:13] offset:2048
	global_load_dwordx4 v[108:111], v5, s[12:13] offset:3072
	s_cmp_eq_u32 s23, 0
	s_cbranch_scc1 .Lg10_a_w8
	s_waitcnt vmcnt(12)
	s_branch .Lg10_a_have

; DI float bflo(unsigned u) { return __uint_as_float(u << 16); }
; DI float bfhi(unsigned u) { return __uint_as_float(u & 0xffff0000u); }
; DI void phase_ret_gate(const Params& p) {
;     ...
;         float o[32]; float ss = 0.f;
; #pragma unroll
;         for (int q = 0; q < 4; ++q) { const u32x4 a = *(const u32x4*)(oraw + (size_t)tok * 2048 + 32 * lane + 8 * q); const unsigned au[4] = {a.x, a.y, a.z, a.w};
; #pragma unroll
;             for (int i = 0; i < 4; ++i) { o[8 * q + 2 * i] = bflo(au[i]); o[8 * q + 2 * i + 1] = bfhi(au[i]); ss += o[8 * q + 2 * i] * o[8 * q + 2 * i] + o[8 * q + 2 * i + 1] * o[8 * q + 2 * i + 1]; } }
;         ss = row16_sum(ss);
;         const float rstd = rsqrtf(ss * (1.f / 512.f) + 1e-6f);
.Lg10_a_have:
	s_mov_b32 s23, 1
	v_lshlrev_b32_e32 v112, 16, v48
	v_and_b32_e32 v113, 0xffff0000, v48
	v_lshlrev_b32_e32 v114, 16, v49
	v_and_b32_e32 v115, 0xffff0000, v49
	v_lshlrev_b32_e32 v116, 16, v50
	v_and_b32_e32 v117, 0xffff0000, v50
	v_lshlrev_b32_e32 v118, 16, v51
	v_and_b32_e32 v119, 0xffff0000, v51
	v_lshlrev_b32_e32 v120, 16, v52
	v_and_b32_e32 v121, 0xffff0000, v52
	v_lshlrev_b32_e32 v122, 16, v53
	v_and_b32_e32 v123, 0xffff0000, v53
	v_lshlrev_b32_e32 v124, 16, v54
	v_and_b32_e32 v125, 0xffff0000, v54
	v_lshlrev_b32_e32 v126, 16, v55
	v_and_b32_e32 v127, 0xffff0000, v55
	v_lshlrev_b32_e32 v128, 16, v56
	v_and_b32_e32 v129, 0xffff0000, v56
	v_lshlrev_b32_e32 v130, 16, v57
	v_and_b32_e32 v131, 0xffff0000, v57
	v_lshlrev_b32_e32 v132, 16, v58
	v_and_b32_e32 v133, 0xffff0000, v58
	v_lshlrev_b32_e32 v134, 16, v59
	v_and_b32_e32 v135, 0xffff0000, v59
	v_lshlrev_b32_e32 v136, 16, v60
	v_and_b32_e32 v137, 0xffff0000, v60
	v_lshlrev_b32_e32 v138, 16, v61
	v_and_b32_e32 v139, 0xffff0000, v61
	v_lshlrev_b32_e32 v140, 16, v62
	v_and_b32_e32 v141, 0xffff0000, v62
	v_lshlrev_b32_e32 v142, 16, v63
	v_and_b32_e32 v143, 0xffff0000, v63
	v_mul_f32_e32 v144, v112, v112
	v_fmac_f32_e32 v144, v113, v113
	v_fmac_f32_e32 v144, v114, v114
	v_fmac_f32_e32 v144, v115, v115
	v_fmac_f32_e32 v144, v116, v116
	v_fmac_f32_e32 v144, v117, v117
	v_fmac_f32_e32 v144, v118, v118
	v_fmac_f32_e32 v144, v119, v119
	v_mul_f32_e32 v145, v120, v120
	v_fmac_f32_e32 v145, v121, v121
	v_fmac_f32_e32 v145, v122, v122
	v_fmac_f32_e32 v145, v123, v123
	v_fmac_f32_e32 v145, v124, v124
	v_fmac_f32_e32 v145, v125, v125
	v_fmac_f32_e32 v145, v126, v126
	v_fmac_f32_e32 v145, v127, v127
	v_mul_f32_e32 v146, v128, v128
	v_fmac_f32_e32 v146, v129, v129
	v_fmac_f32_e32 v146, v130, v130
	v_fmac_f32_e32 v146, v131, v131
	v_fmac_f32_e32 v146, v132, v132
	v_fmac_f32_e32 v146, v133, v133
	v_fmac_f32_e32 v146, v134, v134
	v_fmac_f32_e32 v146, v135, v135
	v_mul_f32_e32 v147, v136, v136
	v_fmac_f32_e32 v147, v137, v137
	v_fmac_f32_e32 v147, v138, v138
	v_fmac_f32_e32 v147, v139, v139
	v_fmac_f32_e32 v147, v140, v140
	v_fmac_f32_e32 v147, v141, v141
	v_fmac_f32_e32 v147, v142, v142
	v_fmac_f32_e32 v147, v143, v143
	v_lshlrev_b32_e32 v198, 16, v64
	v_and_b32_e32 v199, 0xffff0000, v64
	v_lshlrev_b32_e32 v200, 16, v65
	v_and_b32_e32 v201, 0xffff0000, v65
	v_lshlrev_b32_e32 v202, 16, v66
	v_and_b32_e32 v203, 0xffff0000, v66
	v_lshlrev_b32_e32 v204, 16, v67
	v_and_b32_e32 v205, 0xffff0000, v67
	v_lshlrev_b32_e32 v206, 16, v68
	v_and_b32_e32 v207, 0xffff0000, v68
	v_lshlrev_b32_e32 v208, 16, v69
	v_and_b32_e32 v209, 0xffff0000, v69
	v_lshlrev_b32_e32 v210, 16, v70
	v_and_b32_e32 v211, 0xffff0000, v70
	v_lshlrev_b32_e32 v212, 16, v71
	v_and_b32_e32 v213, 0xffff0000, v71
	v_lshlrev_b32_e32 v214, 16, v72
	v_and_b32_e32 v215, 0xffff0000, v72
	v_lshlrev_b32_e32 v216, 16, v73
	v_and_b32_e32 v217, 0xffff0000, v73
	v_lshlrev_b32_e32 v218, 16, v74
	v_and_b32_e32 v219, 0xffff0000, v74
	v_lshlrev_b32_e32 v220, 16, v75
	v_and_b32_e32 v221, 0xffff0000, v75
	v_lshlrev_b32_e32 v222, 16, v76
	v_and_b32_e32 v223, 0xffff0000, v76
	v_lshlrev_b32_e32 v224, 16, v77
	v_and_b32_e32 v225, 0xffff0000, v77
	v_lshlrev_b32_e32 v226, 16, v78
	v_and_b32_e32 v227, 0xffff0000, v78
	v_lshlrev_b32_e32 v228, 16, v79
	v_and_b32_e32 v229, 0xffff0000, v79
	s_nop 0
	v_add_f32_dpp v144, v144, v144 quad_perm:[1,0,3,2] row_mask:0xf bank_mask:0xf bound_ctrl:1
	v_add_f32_dpp v145, v145, v145 quad_perm:[1,0,3,2] row_mask:0xf bank_mask:0xf bound_ctrl:1
	v_add_f32_dpp v146, v146, v146 quad_perm:[1,0,3,2] row_mask:0xf bank_mask:0xf bound_ctrl:1
	v_add_f32_dpp v147, v147, v147 quad_perm:[1,0,3,2] row_mask:0xf bank_mask:0xf bound_ctrl:1
	s_nop 0
	v_add_f32_dpp v144, v144, v144 quad_perm:[2,3,0,1] row_mask:0xf bank_mask:0xf bound_ctrl:1
	v_add_f32_dpp v145, v145, v145 quad_perm:[2,3,0,1] row_mask:0xf bank_mask:0xf bound_ctrl:1
	v_add_f32_dpp v146, v146, v146 quad_perm:[2,3,0,1] row_mask:0xf bank_mask:0xf bound_ctrl:1
	v_add_f32_dpp v147, v147, v147 quad_perm:[2,3,0,1] row_mask:0xf bank_mask:0xf bound_ctrl:1
	s_nop 0
	v_add_f32_dpp v144, v144, v144 row_ror:4 row_mask:0xf bank_mask:0xf bound_ctrl:1
	v_add_f32_dpp v145, v145, v145 row_ror:4 row_mask:0xf bank_mask:0xf bound_ctrl:1
	v_add_f32_dpp v146, v146, v146 row_ror:4 row_mask:0xf bank_mask:0xf bound_ctrl:1
	v_add_f32_dpp v147, v147, v147 row_ror:4 row_mask:0xf bank_mask:0xf bound_ctrl:1
	s_nop 0
	v_add_f32_dpp v144, v144, v144 row_ror:8 row_mask:0xf bank_mask:0xf bound_ctrl:1
	v_add_f32_dpp v145, v145, v145 row_ror:8 row_mask:0xf bank_mask:0xf bound_ctrl:1
	v_add_f32_dpp v146, v146, v146 row_ror:8 row_mask:0xf bank_mask:0xf bound_ctrl:1
	v_add_f32_dpp v147, v147, v147 row_ror:8 row_mask:0xf bank_mask:0xf bound_ctrl:1
	v_readlane_b32 s0, v144, 0
	v_readlane_b32 s1, v144, 16
	v_readlane_b32 s18, v144, 32
	v_readlane_b32 s19, v144, 48
	s_nop 1
	v_mov_b32_e32 v144, s0
	v_add_f32_e32 v144, s1, v144
	v_add_f32_e32 v144, s18, v144
	v_add_f32_e32 v144, s19, v144
	v_fmamk_f32 v144, v144, 0x3b000000, v15
	v_rsq_f32_e32 v144, v144
	v_readlane_b32 s0, v145, 0
	v_readlane_b32 s1, v145, 16
	v_readlane_b32 s18, v145, 32
	v_readlane_b32 s19, v145, 48
	s_nop 1
	v_mov_b32_e32 v145, s0
	v_add_f32_e32 v145, s1, v145
	v_add_f32_e32 v145, s18, v145
	v_add_f32_e32 v145, s19, v145
	v_fmamk_f32 v145, v145, 0x3b000000, v15
	v_rsq_f32_e32 v145, v145
	v_readlane_b32 s0, v146, 0
	v_readlane_b32 s1, v146, 16
	v_readlane_b32 s18, v146, 32
	v_readlane_b32 s19, v146, 48
	s_nop 1
	v_mov_b32_e32 v146, s0
	v_add_f32_e32 v146, s1, v146
	v_add_f32_e32 v146, s18, v146
	v_add_f32_e32 v146, s19, v146
	v_fmamk_f32 v146, v146, 0x3b000000, v15
; DI unsigned pk_bf16(float a, float b) { f32x2 v = {a, b}; bf2_t r = __builtin_convertvector(v, bf2_t); return __builtin_bit_cast(unsigned, r); }
; DI float bflo(unsigned u) { return __uint_as_float(u << 16); }
; DI float bfhi(unsigned u) { return __uint_as_float(u & 0xffff0000u); }
; DI float silu_f(float x) { return x * __builtin_amdgcn_rcpf(1.f + __expf(-x)); }
; DI void phase_ret_gate(const Params& p) {
;     ...
;         const float rstd = rsqrtf(ss * (1.f / 512.f) + 1e-6f);
;     ...
;             for (int i = 0; i < 4; ++i) { const float v0 = o[8 * q + 2 * i] * rstd * wn[8 * q + 2 * i] * silu_f(bflo(gu[i])), v1 = o[8 * q + 2 * i + 1] * rstd * wn[8 * q + 2 * i + 1] * silu_f(bfhi(gu[i])); r[i] = pk_bf16(v0, v1); }
	v_rsq_f32_e32 v146, v146
	v_readlane_b32 s0, v147, 0
	v_readlane_b32 s1, v147, 16
	v_readlane_b32 s18, v147, 32
	v_readlane_b32 s19, v147, 48
	s_nop 1
	v_mov_b32_e32 v147, s0
	v_add_f32_e32 v147, s1, v147
	v_add_f32_e32 v147, s18, v147
	v_add_f32_e32 v147, s19, v147
	v_fmamk_f32 v147, v147, 0x3b000000, v15
	v_rsq_f32_e32 v147, v147
	v_mul_f32_e32 v148, 0xbfb8aa3b, v198
	v_mul_f32_e32 v149, 0xbfb8aa3b, v199
	v_mul_f32_e32 v150, 0xbfb8aa3b, v200
	v_mul_f32_e32 v151, 0xbfb8aa3b, v201
	v_mul_f32_e32 v152, 0xbfb8aa3b, v202
	v_mul_f32_e32 v153, 0xbfb8aa3b, v203
	v_mul_f32_e32 v154, 0xbfb8aa3b, v204
	v_mul_f32_e32 v155, 0xbfb8aa3b, v205
	v_exp_f32_e32 v148, v148
	v_exp_f32_e32 v149, v149
	v_exp_f32_e32 v150, v150
	v_exp_f32_e32 v151, v151
	v_exp_f32_e32 v152, v152
	v_exp_f32_e32 v153, v153
	v_exp_f32_e32 v154, v154
	v_exp_f32_e32 v155, v155
	v_add_f32_e32 v148, 1.0, v148
	v_add_f32_e32 v149, 1.0, v149
	v_add_f32_e32 v150, 1.0, v150
	v_add_f32_e32 v151, 1.0, v151
	v_add_f32_e32 v152, 1.0, v152
	v_add_f32_e32 v153, 1.0, v153
	v_add_f32_e32 v154, 1.0, v154
	v_add_f32_e32 v155, 1.0, v155
	v_rcp_f32_e32 v148, v148
	v_rcp_f32_e32 v149, v149
	v_rcp_f32_e32 v150, v150
	v_rcp_f32_e32 v151, v151
	v_rcp_f32_e32 v152, v152
	v_rcp_f32_e32 v153, v153
	v_rcp_f32_e32 v154, v154
	v_rcp_f32_e32 v155, v155
	v_mul_f32_e32 v198, v148, v198
	v_mul_f32_e32 v199, v149, v199
	v_mul_f32_e32 v200, v150, v200
	v_mul_f32_e32 v201, v151, v201
	v_mul_f32_e32 v202, v152, v202
	v_mul_f32_e32 v203, v153, v203
	v_mul_f32_e32 v204, v154, v204
	v_mul_f32_e32 v205, v155, v205
	v_mul_f32_e32 v148, 0xbfb8aa3b, v206
	v_mul_f32_e32 v149, 0xbfb8aa3b, v207
	v_mul_f32_e32 v150, 0xbfb8aa3b, v208
	v_mul_f32_e32 v151, 0xbfb8aa3b, v209
	v_mul_f32_e32 v152, 0xbfb8aa3b, v210
	v_mul_f32_e32 v153, 0xbfb8aa3b, v211
	v_mul_f32_e32 v154, 0xbfb8aa3b, v212
	v_mul_f32_e32 v155, 0xbfb8aa3b, v213
	v_exp_f32_e32 v148, v148
	v_exp_f32_e32 v149, v149
	v_exp_f32_e32 v150, v150
	v_exp_f32_e32 v151, v151
	v_exp_f32_e32 v152, v152
	v_exp_f32_e32 v153, v153
	v_exp_f32_e32 v154, v154
	v_exp_f32_e32 v155, v155
	v_add_f32_e32 v148, 1.0, v148
	v_add_f32_e32 v149, 1.0, v149
	v_add_f32_e32 v150, 1.0, v150
	v_add_f32_e32 v151, 1.0, v151
	v_add_f32_e32 v152, 1.0, v152
	v_add_f32_e32 v153, 1.0, v153
	v_add_f32_e32 v154, 1.0, v154
	v_add_f32_e32 v155, 1.0, v155
	v_rcp_f32_e32 v148, v148
	v_rcp_f32_e32 v149, v149
	v_rcp_f32_e32 v150, v150
	v_rcp_f32_e32 v151, v151
	v_rcp_f32_e32 v152, v152
	v_rcp_f32_e32 v153, v153
	v_rcp_f32_e32 v154, v154
	v_rcp_f32_e32 v155, v155
	v_mul_f32_e32 v206, v148, v206
	v_mul_f32_e32 v207, v149, v207
	v_mul_f32_e32 v208, v150, v208
	v_mul_f32_e32 v209, v151, v209
	v_mul_f32_e32 v210, v152, v210
	v_mul_f32_e32 v211, v153, v211
	v_mul_f32_e32 v212, v154, v212
	v_mul_f32_e32 v213, v155, v213
	v_mul_f32_e32 v148, 0xbfb8aa3b, v214
	v_mul_f32_e32 v149, 0xbfb8aa3b, v215
	v_mul_f32_e32 v150, 0xbfb8aa3b, v216
	v_mul_f32_e32 v151, 0xbfb8aa3b, v217
	v_mul_f32_e32 v152, 0xbfb8aa3b, v218
	v_mul_f32_e32 v153, 0xbfb8aa3b, v219
	v_mul_f32_e32 v154, 0xbfb8aa3b, v220
	v_mul_f32_e32 v155, 0xbfb8aa3b, v221
	v_exp_f32_e32 v148, v148
	v_exp_f32_e32 v149, v149
	v_exp_f32_e32 v150, v150
	v_exp_f32_e32 v151, v151
	v_exp_f32_e32 v152, v152
	v_exp_f32_e32 v153, v153
	v_exp_f32_e32 v154, v154
	v_exp_f32_e32 v155, v155
	v_add_f32_e32 v148, 1.0, v148
	v_add_f32_e32 v149, 1.0, v149
	v_add_f32_e32 v150, 1.0, v150
	v_add_f32_e32 v151, 1.0, v151
	v_add_f32_e32 v152, 1.0, v152
	v_add_f32_e32 v153, 1.0, v153
	v_add_f32_e32 v154, 1.0, v154
	v_add_f32_e32 v155, 1.0, v155
	v_rcp_f32_e32 v148, v148
	v_rcp_f32_e32 v149, v149
	v_rcp_f32_e32 v150, v150
	v_rcp_f32_e32 v151, v151
	v_rcp_f32_e32 v152, v152
	v_rcp_f32_e32 v153, v153
	v_rcp_f32_e32 v154, v154
	v_rcp_f32_e32 v155, v155
	v_mul_f32_e32 v214, v148, v214
	v_mul_f32_e32 v215, v149, v215
	v_mul_f32_e32 v216, v150, v216
	v_mul_f32_e32 v217, v151, v217
	v_mul_f32_e32 v218, v152, v218
	v_mul_f32_e32 v219, v153, v219
	v_mul_f32_e32 v220, v154, v220
	v_mul_f32_e32 v221, v155, v221
	v_mul_f32_e32 v148, 0xbfb8aa3b, v222
	v_mul_f32_e32 v149, 0xbfb8aa3b, v223
	v_mul_f32_e32 v150, 0xbfb8aa3b, v224
	v_mul_f32_e32 v151, 0xbfb8aa3b, v225
	v_mul_f32_e32 v152, 0xbfb8aa3b, v226
	v_mul_f32_e32 v153, 0xbfb8aa3b, v227
	v_mul_f32_e32 v154, 0xbfb8aa3b, v228
	v_mul_f32_e32 v155, 0xbfb8aa3b, v229
	v_exp_f32_e32 v148, v148
	v_exp_f32_e32 v149, v149
	v_exp_f32_e32 v150, v150
	v_exp_f32_e32 v151, v151
	v_exp_f32_e32 v152, v152
	v_exp_f32_e32 v153, v153
	v_exp_f32_e32 v154, v154
	v_exp_f32_e32 v155, v155
	v_add_f32_e32 v148, 1.0, v148
	v_add_f32_e32 v149, 1.0, v149
	v_add_f32_e32 v150, 1.0, v150
	v_add_f32_e32 v151, 1.0, v151
	v_add_f32_e32 v152, 1.0, v152
	v_add_f32_e32 v153, 1.0, v153
	v_add_f32_e32 v154, 1.0, v154
	v_add_f32_e32 v155, 1.0, v155
	v_rcp_f32_e32 v148, v148
	v_rcp_f32_e32 v149, v149
	v_rcp_f32_e32 v150, v150
	v_rcp_f32_e32 v151, v151
	v_rcp_f32_e32 v152, v152
	v_rcp_f32_e32 v153, v153
	v_rcp_f32_e32 v154, v154
	v_rcp_f32_e32 v155, v155
	v_mul_f32_e32 v222, v148, v222
; DI unsigned pk_bf16(float a, float b) { f32x2 v = {a, b}; bf2_t r = __builtin_convertvector(v, bf2_t); return __builtin_bit_cast(unsigned, r); }
; DI float bflo(unsigned u) { return __uint_as_float(u << 16); }
; DI float bfhi(unsigned u) { return __uint_as_float(u & 0xffff0000u); }
; DI float silu_f(float x) { return x * __builtin_amdgcn_rcpf(1.f + __expf(-x)); }
; DI void phase_ret_gate(const Params& p) {
;     ...
;     for (int tok = gw; tok < T_TOK; tok += nw) {
;         float o[32]; float ss = 0.f;
; #pragma unroll
;         for (int q = 0; q < 4; ++q) { const u32x4 a = *(const u32x4*)(oraw + (size_t)tok * 2048 + 32 * lane + 8 * q); const unsigned au[4] = {a.x, a.y, a.z, a.w};
; #pragma unroll
;             for (int i = 0; i < 4; ++i) { o[8 * q + 2 * i] = bflo(au[i]); o[8 * q + 2 * i + 1] = bfhi(au[i]); ss += o[8 * q + 2 * i] * o[8 * q + 2 * i] + o[8 * q + 2 * i + 1] * o[8 * q + 2 * i + 1]; } }
;         ss = row16_sum(ss);
;         const float rstd = rsqrtf(ss * (1.f / 512.f) + 1e-6f);
;         const float* wn = p.onorm_b + 32 * lane;
; #pragma unroll
;         for (int q = 0; q < 4; ++q) { const u32x4 g = *(const u32x4*)(P1 + (size_t)tok * LDP1 + 4096 + 32 * lane + 8 * q); const unsigned gu[4] = {g.x, g.y, g.z, g.w}; unsigned r[4];
; #pragma unroll
;             for (int i = 0; i < 4; ++i) { const float v0 = o[8 * q + 2 * i] * rstd * wn[8 * q + 2 * i] * silu_f(bflo(gu[i])), v1 = o[8 * q + 2 * i + 1] * rstd * wn[8 * q + 2 * i + 1] * silu_f(bfhi(gu[i])); r[i] = pk_bf16(v0, v1); }
;             *(u32x4*)(og + (size_t)tok * 2048 + 32 * lane + 8 * q) = (u32x4){r[0], r[1], r[2], r[3]}; }
	v_mul_f32_e32 v223, v149, v223
	v_mul_f32_e32 v224, v150, v224
	v_mul_f32_e32 v225, v151, v225
	v_mul_f32_e32 v226, v152, v226
	v_mul_f32_e32 v227, v153, v227
	v_mul_f32_e32 v228, v154, v228
	v_mul_f32_e32 v229, v155, v229
	s_lshl_b32 s9, s8, 12
	s_add_u32 s20, s16, s9
	s_addc_u32 s21, s17, 0
	v_mul_f32_e32 v112, v144, v112
	v_mul_f32_e32 v113, v144, v113
	v_mul_f32_e32 v114, v144, v114
	v_mul_f32_e32 v115, v144, v115
	v_mul_f32_e32 v116, v144, v116
	v_mul_f32_e32 v117, v144, v117
	v_mul_f32_e32 v118, v144, v118
	v_mul_f32_e32 v119, v144, v119
	v_mul_f32_e32 v112, v16, v112
	v_mul_f32_e32 v113, v17, v113
	v_mul_f32_e32 v114, v18, v114
	v_mul_f32_e32 v115, v19, v115
	v_mul_f32_e32 v116, v20, v116
	v_mul_f32_e32 v117, v21, v117
	v_mul_f32_e32 v118, v22, v118
	v_mul_f32_e32 v119, v23, v119
	v_mul_f32_e32 v112, v198, v112
	v_mul_f32_e32 v113, v199, v113
	v_mul_f32_e32 v114, v200, v114
	v_mul_f32_e32 v115, v201, v115
	v_mul_f32_e32 v116, v202, v116
	v_mul_f32_e32 v117, v203, v117
	v_mul_f32_e32 v118, v204, v118
	v_mul_f32_e32 v119, v205, v119
	v_cvt_pk_bf16_f32 v148, v112, v113
	v_cvt_pk_bf16_f32 v149, v114, v115
	v_cvt_pk_bf16_f32 v150, v116, v117
	v_cvt_pk_bf16_f32 v151, v118, v119
	s_nop 0
	global_store_dwordx4 v2, v[148:151], s[20:21]
	s_nop 1
	v_mul_f32_e32 v120, v145, v120
	v_mul_f32_e32 v121, v145, v121
	v_mul_f32_e32 v122, v145, v122
	v_mul_f32_e32 v123, v145, v123
	v_mul_f32_e32 v124, v145, v124
	v_mul_f32_e32 v125, v145, v125
	v_mul_f32_e32 v126, v145, v126
	v_mul_f32_e32 v127, v145, v127
	v_mul_f32_e32 v120, v24, v120
	v_mul_f32_e32 v121, v25, v121
	v_mul_f32_e32 v122, v26, v122
	v_mul_f32_e32 v123, v27, v123
	v_mul_f32_e32 v124, v28, v124
	v_mul_f32_e32 v125, v29, v125
	v_mul_f32_e32 v126, v30, v126
	v_mul_f32_e32 v127, v31, v127
	v_mul_f32_e32 v120, v206, v120
	v_mul_f32_e32 v121, v207, v121
	v_mul_f32_e32 v122, v208, v122
	v_mul_f32_e32 v123, v209, v123
	v_mul_f32_e32 v124, v210, v124
	v_mul_f32_e32 v125, v211, v125
	v_mul_f32_e32 v126, v212, v126
	v_mul_f32_e32 v127, v213, v127
	v_cvt_pk_bf16_f32 v148, v120, v121
	v_cvt_pk_bf16_f32 v149, v122, v123
	v_cvt_pk_bf16_f32 v150, v124, v125
	v_cvt_pk_bf16_f32 v151, v126, v127
	s_nop 0
	global_store_dwordx4 v2, v[148:151], s[20:21] offset:1024
	s_nop 1
	v_mul_f32_e32 v128, v146, v128
	v_mul_f32_e32 v129, v146, v129
	v_mul_f32_e32 v130, v146, v130
	v_mul_f32_e32 v131, v146, v131
	v_mul_f32_e32 v132, v146, v132
	v_mul_f32_e32 v133, v146, v133
	v_mul_f32_e32 v134, v146, v134
	v_mul_f32_e32 v135, v146, v135
	v_mul_f32_e32 v128, v32, v128
	v_mul_f32_e32 v129, v33, v129
	v_mul_f32_e32 v130, v34, v130
	v_mul_f32_e32 v131, v35, v131
	v_mul_f32_e32 v132, v36, v132
	v_mul_f32_e32 v133, v37, v133
	v_mul_f32_e32 v134, v38, v134
	v_mul_f32_e32 v135, v39, v135
	v_mul_f32_e32 v128, v214, v128
	v_mul_f32_e32 v129, v215, v129
	v_mul_f32_e32 v130, v216, v130
	v_mul_f32_e32 v131, v217, v131
	v_mul_f32_e32 v132, v218, v132
	v_mul_f32_e32 v133, v219, v133
	v_mul_f32_e32 v134, v220, v134
	v_mul_f32_e32 v135, v221, v135
	v_cvt_pk_bf16_f32 v148, v128, v129
	v_cvt_pk_bf16_f32 v149, v130, v131
	v_cvt_pk_bf16_f32 v150, v132, v133
	v_cvt_pk_bf16_f32 v151, v134, v135
	s_nop 0
	global_store_dwordx4 v2, v[148:151], s[20:21] offset:2048
	s_nop 1
	v_mul_f32_e32 v136, v147, v136
	v_mul_f32_e32 v137, v147, v137
	v_mul_f32_e32 v138, v147, v138
	v_mul_f32_e32 v139, v147, v139
	v_mul_f32_e32 v140, v147, v140
	v_mul_f32_e32 v141, v147, v141
	v_mul_f32_e32 v142, v147, v142
	v_mul_f32_e32 v143, v147, v143
	v_mul_f32_e32 v136, v40, v136
	v_mul_f32_e32 v137, v41, v137
	v_mul_f32_e32 v138, v42, v138
	v_mul_f32_e32 v139, v43, v139
	v_mul_f32_e32 v140, v44, v140
	v_mul_f32_e32 v141, v45, v141
	v_mul_f32_e32 v142, v46, v142
	v_mul_f32_e32 v143, v47, v143
	v_mul_f32_e32 v136, v222, v136
	v_mul_f32_e32 v137, v223, v137
	v_mul_f32_e32 v138, v224, v138
	v_mul_f32_e32 v139, v225, v139
	v_mul_f32_e32 v140, v226, v140
	v_mul_f32_e32 v141, v227, v141
	v_mul_f32_e32 v142, v228, v142
	v_mul_f32_e32 v143, v229, v143
	v_cvt_pk_bf16_f32 v148, v136, v137
	v_cvt_pk_bf16_f32 v149, v138, v139
	v_cvt_pk_bf16_f32 v150, v140, v141
	v_cvt_pk_bf16_f32 v151, v142, v143
	s_nop 0
	global_store_dwordx4 v2, v[148:151], s[20:21] offset:3072
	s_nop 1
	s_mov_b32 s8, s22
	s_cmp_lt_u32 s8, 0x4400
	s_cbranch_scc0 .Lg10_done
.Lg10_b:
	s_add_u32 s22, s8, s46
	s_cmp_lt_u32 s22, 0x4400
	s_cbranch_scc0 .Lg10_b_nonext
	s_lshl_b32 s9, s22, 12
	v_add_u32_e32 v4, s9, v2
	s_mul_i32 s9, s22, 0x3000
	v_add_u32_e32 v5, s9, v2
	global_load_dwordx4 v[48:51], v4, s[10:11]
	global_load_dwordx4 v[52:55], v4, s[10:11] offset:1024
	global_load_dwordx4 v[56:59], v4, s[10:11] offset:2048
	global_load_dwordx4 v[60:63], v4, s[10:11] offset:3072
	global_load_dwordx4 v[64:67], v5, s[12:13]
	global_load_dwordx4 v[68:71], v5, s[12:13] offset:1024
	global_load_dwordx4 v[72:75], v5, s[12:13] offset:2048
	global_load_dwordx4 v[76:79], v5, s[12:13] offset:3072
	s_cmp_eq_u32 s23, 0
	s_cbranch_scc1 .Lg10_b_w8
	s_waitcnt vmcnt(12)
	s_branch .Lg10_b_have

; DI float bflo(unsigned u) { return __uint_as_float(u << 16); }
; DI float bfhi(unsigned u) { return __uint_as_float(u & 0xffff0000u); }
; DI void phase_ret_gate(const Params& p) {
;     ...
; #pragma unroll
;         for (int q = 0; q < 4; ++q) { const u32x4 a = *(const u32x4*)(oraw + (size_t)tok * 2048 + 32 * lane + 8 * q); const unsigned au[4] = {a.x, a.y, a.z, a.w};
; #pragma unroll
;             for (int i = 0; i < 4; ++i) { o[8 * q + 2 * i] = bflo(au[i]); o[8 * q + 2 * i + 1] = bfhi(au[i]); ss += o[8 * q + 2 * i] * o[8 * q + 2 * i] + o[8 * q + 2 * i + 1] * o[8 * q + 2 * i + 1]; } }
;         ss = row16_sum(ss);
;         const float rstd = rsqrtf(ss * (1.f / 512.f) + 1e-6f);
.Lg10_b_have:
	s_mov_b32 s23, 1
	v_lshlrev_b32_e32 v112, 16, v80
	v_and_b32_e32 v113, 0xffff0000, v80
	v_lshlrev_b32_e32 v114, 16, v81
	v_and_b32_e32 v115, 0xffff0000, v81
	v_lshlrev_b32_e32 v116, 16, v82
	v_and_b32_e32 v117, 0xffff0000, v82
	v_lshlrev_b32_e32 v118, 16, v83
	v_and_b32_e32 v119, 0xffff0000, v83
	v_lshlrev_b32_e32 v120, 16, v84
	v_and_b32_e32 v121, 0xffff0000, v84
	v_lshlrev_b32_e32 v122, 16, v85
	v_and_b32_e32 v123, 0xffff0000, v85
	v_lshlrev_b32_e32 v124, 16, v86
	v_and_b32_e32 v125, 0xffff0000, v86
	v_lshlrev_b32_e32 v126, 16, v87
	v_and_b32_e32 v127, 0xffff0000, v87
	v_lshlrev_b32_e32 v128, 16, v88
	v_and_b32_e32 v129, 0xffff0000, v88
	v_lshlrev_b32_e32 v130, 16, v89
	v_and_b32_e32 v131, 0xffff0000, v89
	v_lshlrev_b32_e32 v132, 16, v90
	v_and_b32_e32 v133, 0xffff0000, v90
	v_lshlrev_b32_e32 v134, 16, v91
	v_and_b32_e32 v135, 0xffff0000, v91
	v_lshlrev_b32_e32 v136, 16, v92
	v_and_b32_e32 v137, 0xffff0000, v92
	v_lshlrev_b32_e32 v138, 16, v93
	v_and_b32_e32 v139, 0xffff0000, v93
	v_lshlrev_b32_e32 v140, 16, v94
	v_and_b32_e32 v141, 0xffff0000, v94
	v_lshlrev_b32_e32 v142, 16, v95
	v_and_b32_e32 v143, 0xffff0000, v95
	v_mul_f32_e32 v144, v112, v112
	v_fmac_f32_e32 v144, v113, v113
	v_fmac_f32_e32 v144, v114, v114
	v_fmac_f32_e32 v144, v115, v115
	v_fmac_f32_e32 v144, v116, v116
	v_fmac_f32_e32 v144, v117, v117
	v_fmac_f32_e32 v144, v118, v118
	v_fmac_f32_e32 v144, v119, v119
	v_mul_f32_e32 v145, v120, v120
	v_fmac_f32_e32 v145, v121, v121
	v_fmac_f32_e32 v145, v122, v122
	v_fmac_f32_e32 v145, v123, v123
	v_fmac_f32_e32 v145, v124, v124
	v_fmac_f32_e32 v145, v125, v125
	v_fmac_f32_e32 v145, v126, v126
	v_fmac_f32_e32 v145, v127, v127
	v_mul_f32_e32 v146, v128, v128
	v_fmac_f32_e32 v146, v129, v129
	v_fmac_f32_e32 v146, v130, v130
	v_fmac_f32_e32 v146, v131, v131
	v_fmac_f32_e32 v146, v132, v132
	v_fmac_f32_e32 v146, v133, v133
	v_fmac_f32_e32 v146, v134, v134
	v_fmac_f32_e32 v146, v135, v135
	v_mul_f32_e32 v147, v136, v136
	v_fmac_f32_e32 v147, v137, v137
	v_fmac_f32_e32 v147, v138, v138
	v_fmac_f32_e32 v147, v139, v139
	v_fmac_f32_e32 v147, v140, v140
	v_fmac_f32_e32 v147, v141, v141
	v_fmac_f32_e32 v147, v142, v142
	v_fmac_f32_e32 v147, v143, v143
	v_lshlrev_b32_e32 v198, 16, v96
	v_and_b32_e32 v199, 0xffff0000, v96
	v_lshlrev_b32_e32 v200, 16, v97
	v_and_b32_e32 v201, 0xffff0000, v97
	v_lshlrev_b32_e32 v202, 16, v98
	v_and_b32_e32 v203, 0xffff0000, v98
	v_lshlrev_b32_e32 v204, 16, v99
	v_and_b32_e32 v205, 0xffff0000, v99
	v_lshlrev_b32_e32 v206, 16, v100
	v_and_b32_e32 v207, 0xffff0000, v100
	v_lshlrev_b32_e32 v208, 16, v101
	v_and_b32_e32 v209, 0xffff0000, v101
	v_lshlrev_b32_e32 v210, 16, v102
	v_and_b32_e32 v211, 0xffff0000, v102
	v_lshlrev_b32_e32 v212, 16, v103
	v_and_b32_e32 v213, 0xffff0000, v103
	v_lshlrev_b32_e32 v214, 16, v104
	v_and_b32_e32 v215, 0xffff0000, v104
	v_lshlrev_b32_e32 v216, 16, v105
	v_and_b32_e32 v217, 0xffff0000, v105
	v_lshlrev_b32_e32 v218, 16, v106
	v_and_b32_e32 v219, 0xffff0000, v106
	v_lshlrev_b32_e32 v220, 16, v107
	v_and_b32_e32 v221, 0xffff0000, v107
	v_lshlrev_b32_e32 v222, 16, v108
	v_and_b32_e32 v223, 0xffff0000, v108
	v_lshlrev_b32_e32 v224, 16, v109
	v_and_b32_e32 v225, 0xffff0000, v109
	v_lshlrev_b32_e32 v226, 16, v110
	v_and_b32_e32 v227, 0xffff0000, v110
	v_lshlrev_b32_e32 v228, 16, v111
	v_and_b32_e32 v229, 0xffff0000, v111
	s_nop 0
	v_add_f32_dpp v144, v144, v144 quad_perm:[1,0,3,2] row_mask:0xf bank_mask:0xf bound_ctrl:1
	v_add_f32_dpp v145, v145, v145 quad_perm:[1,0,3,2] row_mask:0xf bank_mask:0xf bound_ctrl:1
	v_add_f32_dpp v146, v146, v146 quad_perm:[1,0,3,2] row_mask:0xf bank_mask:0xf bound_ctrl:1
	v_add_f32_dpp v147, v147, v147 quad_perm:[1,0,3,2] row_mask:0xf bank_mask:0xf bound_ctrl:1
	s_nop 0
	v_add_f32_dpp v144, v144, v144 quad_perm:[2,3,0,1] row_mask:0xf bank_mask:0xf bound_ctrl:1
	v_add_f32_dpp v145, v145, v145 quad_perm:[2,3,0,1] row_mask:0xf bank_mask:0xf bound_ctrl:1
	v_add_f32_dpp v146, v146, v146 quad_perm:[2,3,0,1] row_mask:0xf bank_mask:0xf bound_ctrl:1
	v_add_f32_dpp v147, v147, v147 quad_perm:[2,3,0,1] row_mask:0xf bank_mask:0xf bound_ctrl:1
	s_nop 0
	v_add_f32_dpp v144, v144, v144 row_ror:4 row_mask:0xf bank_mask:0xf bound_ctrl:1
	v_add_f32_dpp v145, v145, v145 row_ror:4 row_mask:0xf bank_mask:0xf bound_ctrl:1
	v_add_f32_dpp v146, v146, v146 row_ror:4 row_mask:0xf bank_mask:0xf bound_ctrl:1
	v_add_f32_dpp v147, v147, v147 row_ror:4 row_mask:0xf bank_mask:0xf bound_ctrl:1
	s_nop 0
	v_add_f32_dpp v144, v144, v144 row_ror:8 row_mask:0xf bank_mask:0xf bound_ctrl:1
	v_add_f32_dpp v145, v145, v145 row_ror:8 row_mask:0xf bank_mask:0xf bound_ctrl:1
	v_add_f32_dpp v146, v146, v146 row_ror:8 row_mask:0xf bank_mask:0xf bound_ctrl:1
	v_add_f32_dpp v147, v147, v147 row_ror:8 row_mask:0xf bank_mask:0xf bound_ctrl:1
	v_readlane_b32 s0, v144, 0
	v_readlane_b32 s1, v144, 16
	v_readlane_b32 s18, v144, 32
	v_readlane_b32 s19, v144, 48
	s_nop 1
	v_mov_b32_e32 v144, s0
	v_add_f32_e32 v144, s1, v144
	v_add_f32_e32 v144, s18, v144
	v_add_f32_e32 v144, s19, v144
	v_fmamk_f32 v144, v144, 0x3b000000, v15
	v_rsq_f32_e32 v144, v144
	v_readlane_b32 s0, v145, 0
	v_readlane_b32 s1, v145, 16
	v_readlane_b32 s18, v145, 32
	v_readlane_b32 s19, v145, 48
	s_nop 1
	v_mov_b32_e32 v145, s0
	v_add_f32_e32 v145, s1, v145
	v_add_f32_e32 v145, s18, v145
	v_add_f32_e32 v145, s19, v145
	v_fmamk_f32 v145, v145, 0x3b000000, v15
	v_rsq_f32_e32 v145, v145
	v_readlane_b32 s0, v146, 0
	v_readlane_b32 s1, v146, 16
	v_readlane_b32 s18, v146, 32
	v_readlane_b32 s19, v146, 48
	s_nop 1
	v_mov_b32_e32 v146, s0
	v_add_f32_e32 v146, s1, v146
	v_add_f32_e32 v146, s18, v146
	v_add_f32_e32 v146, s19, v146
; DI unsigned pk_bf16(float a, float b) { f32x2 v = {a, b}; bf2_t r = __builtin_convertvector(v, bf2_t); return __builtin_bit_cast(unsigned, r); }
; DI float bflo(unsigned u) { return __uint_as_float(u << 16); }
; DI float bfhi(unsigned u) { return __uint_as_float(u & 0xffff0000u); }
; DI float silu_f(float x) { return x * __builtin_amdgcn_rcpf(1.f + __expf(-x)); }
; DI void phase_ret_gate(const Params& p) {
;     ...
;         ss = row16_sum(ss);
;         const float rstd = rsqrtf(ss * (1.f / 512.f) + 1e-6f);
;         const float* wn = p.onorm_b + 32 * lane;
; #pragma unroll
;         for (int q = 0; q < 4; ++q) { const u32x4 g = *(const u32x4*)(P1 + (size_t)tok * LDP1 + 4096 + 32 * lane + 8 * q); const unsigned gu[4] = {g.x, g.y, g.z, g.w}; unsigned r[4];
; #pragma unroll
;             for (int i = 0; i < 4; ++i) { const float v0 = o[8 * q + 2 * i] * rstd * wn[8 * q + 2 * i] * silu_f(bflo(gu[i])), v1 = o[8 * q + 2 * i + 1] * rstd * wn[8 * q + 2 * i + 1] * silu_f(bfhi(gu[i])); r[i] = pk_bf16(v0, v1); }
	v_fmamk_f32 v146, v146, 0x3b000000, v15
	v_rsq_f32_e32 v146, v146
	v_readlane_b32 s0, v147, 0
	v_readlane_b32 s1, v147, 16
	v_readlane_b32 s18, v147, 32
	v_readlane_b32 s19, v147, 48
	s_nop 1
	v_mov_b32_e32 v147, s0
	v_add_f32_e32 v147, s1, v147
	v_add_f32_e32 v147, s18, v147
	v_add_f32_e32 v147, s19, v147
	v_fmamk_f32 v147, v147, 0x3b000000, v15
	v_rsq_f32_e32 v147, v147
	v_mul_f32_e32 v148, 0xbfb8aa3b, v198
	v_mul_f32_e32 v149, 0xbfb8aa3b, v199
	v_mul_f32_e32 v150, 0xbfb8aa3b, v200
	v_mul_f32_e32 v151, 0xbfb8aa3b, v201
	v_mul_f32_e32 v152, 0xbfb8aa3b, v202
	v_mul_f32_e32 v153, 0xbfb8aa3b, v203
	v_mul_f32_e32 v154, 0xbfb8aa3b, v204
	v_mul_f32_e32 v155, 0xbfb8aa3b, v205
	v_exp_f32_e32 v148, v148
	v_exp_f32_e32 v149, v149
	v_exp_f32_e32 v150, v150
	v_exp_f32_e32 v151, v151
	v_exp_f32_e32 v152, v152
	v_exp_f32_e32 v153, v153
	v_exp_f32_e32 v154, v154
	v_exp_f32_e32 v155, v155
	v_add_f32_e32 v148, 1.0, v148
	v_add_f32_e32 v149, 1.0, v149
	v_add_f32_e32 v150, 1.0, v150
	v_add_f32_e32 v151, 1.0, v151
	v_add_f32_e32 v152, 1.0, v152
	v_add_f32_e32 v153, 1.0, v153
	v_add_f32_e32 v154, 1.0, v154
	v_add_f32_e32 v155, 1.0, v155
	v_rcp_f32_e32 v148, v148
	v_rcp_f32_e32 v149, v149
	v_rcp_f32_e32 v150, v150
	v_rcp_f32_e32 v151, v151
	v_rcp_f32_e32 v152, v152
	v_rcp_f32_e32 v153, v153
	v_rcp_f32_e32 v154, v154
	v_rcp_f32_e32 v155, v155
	v_mul_f32_e32 v198, v148, v198
	v_mul_f32_e32 v199, v149, v199
	v_mul_f32_e32 v200, v150, v200
	v_mul_f32_e32 v201, v151, v201
	v_mul_f32_e32 v202, v152, v202
	v_mul_f32_e32 v203, v153, v203
	v_mul_f32_e32 v204, v154, v204
	v_mul_f32_e32 v205, v155, v205
	v_mul_f32_e32 v148, 0xbfb8aa3b, v206
	v_mul_f32_e32 v149, 0xbfb8aa3b, v207
	v_mul_f32_e32 v150, 0xbfb8aa3b, v208
	v_mul_f32_e32 v151, 0xbfb8aa3b, v209
	v_mul_f32_e32 v152, 0xbfb8aa3b, v210
	v_mul_f32_e32 v153, 0xbfb8aa3b, v211
	v_mul_f32_e32 v154, 0xbfb8aa3b, v212
	v_mul_f32_e32 v155, 0xbfb8aa3b, v213
	v_exp_f32_e32 v148, v148
	v_exp_f32_e32 v149, v149
	v_exp_f32_e32 v150, v150
	v_exp_f32_e32 v151, v151
	v_exp_f32_e32 v152, v152
	v_exp_f32_e32 v153, v153
	v_exp_f32_e32 v154, v154
	v_exp_f32_e32 v155, v155
	v_add_f32_e32 v148, 1.0, v148
	v_add_f32_e32 v149, 1.0, v149
	v_add_f32_e32 v150, 1.0, v150
	v_add_f32_e32 v151, 1.0, v151
	v_add_f32_e32 v152, 1.0, v152
	v_add_f32_e32 v153, 1.0, v153
	v_add_f32_e32 v154, 1.0, v154
	v_add_f32_e32 v155, 1.0, v155
	v_rcp_f32_e32 v148, v148
	v_rcp_f32_e32 v149, v149
	v_rcp_f32_e32 v150, v150
	v_rcp_f32_e32 v151, v151
	v_rcp_f32_e32 v152, v152
	v_rcp_f32_e32 v153, v153
	v_rcp_f32_e32 v154, v154
	v_rcp_f32_e32 v155, v155
	v_mul_f32_e32 v206, v148, v206
	v_mul_f32_e32 v207, v149, v207
	v_mul_f32_e32 v208, v150, v208
	v_mul_f32_e32 v209, v151, v209
	v_mul_f32_e32 v210, v152, v210
	v_mul_f32_e32 v211, v153, v211
	v_mul_f32_e32 v212, v154, v212
	v_mul_f32_e32 v213, v155, v213
	v_mul_f32_e32 v148, 0xbfb8aa3b, v214
	v_mul_f32_e32 v149, 0xbfb8aa3b, v215
	v_mul_f32_e32 v150, 0xbfb8aa3b, v216
	v_mul_f32_e32 v151, 0xbfb8aa3b, v217
	v_mul_f32_e32 v152, 0xbfb8aa3b, v218
	v_mul_f32_e32 v153, 0xbfb8aa3b, v219
	v_mul_f32_e32 v154, 0xbfb8aa3b, v220
	v_mul_f32_e32 v155, 0xbfb8aa3b, v221
	v_exp_f32_e32 v148, v148
	v_exp_f32_e32 v149, v149
	v_exp_f32_e32 v150, v150
	v_exp_f32_e32 v151, v151
	v_exp_f32_e32 v152, v152
	v_exp_f32_e32 v153, v153
	v_exp_f32_e32 v154, v154
	v_exp_f32_e32 v155, v155
	v_add_f32_e32 v148, 1.0, v148
	v_add_f32_e32 v149, 1.0, v149
	v_add_f32_e32 v150, 1.0, v150
	v_add_f32_e32 v151, 1.0, v151
	v_add_f32_e32 v152, 1.0, v152
	v_add_f32_e32 v153, 1.0, v153
	v_add_f32_e32 v154, 1.0, v154
	v_add_f32_e32 v155, 1.0, v155
	v_rcp_f32_e32 v148, v148
	v_rcp_f32_e32 v149, v149
	v_rcp_f32_e32 v150, v150
	v_rcp_f32_e32 v151, v151
	v_rcp_f32_e32 v152, v152
	v_rcp_f32_e32 v153, v153
	v_rcp_f32_e32 v154, v154
	v_rcp_f32_e32 v155, v155
	v_mul_f32_e32 v214, v148, v214
	v_mul_f32_e32 v215, v149, v215
	v_mul_f32_e32 v216, v150, v216
	v_mul_f32_e32 v217, v151, v217
	v_mul_f32_e32 v218, v152, v218
	v_mul_f32_e32 v219, v153, v219
	v_mul_f32_e32 v220, v154, v220
	v_mul_f32_e32 v221, v155, v221
	v_mul_f32_e32 v148, 0xbfb8aa3b, v222
	v_mul_f32_e32 v149, 0xbfb8aa3b, v223
	v_mul_f32_e32 v150, 0xbfb8aa3b, v224
	v_mul_f32_e32 v151, 0xbfb8aa3b, v225
	v_mul_f32_e32 v152, 0xbfb8aa3b, v226
	v_mul_f32_e32 v153, 0xbfb8aa3b, v227
	v_mul_f32_e32 v154, 0xbfb8aa3b, v228
	v_mul_f32_e32 v155, 0xbfb8aa3b, v229
	v_exp_f32_e32 v148, v148
	v_exp_f32_e32 v149, v149
	v_exp_f32_e32 v150, v150
	v_exp_f32_e32 v151, v151
	v_exp_f32_e32 v152, v152
	v_exp_f32_e32 v153, v153
	v_exp_f32_e32 v154, v154
	v_exp_f32_e32 v155, v155
	v_add_f32_e32 v148, 1.0, v148
	v_add_f32_e32 v149, 1.0, v149
	v_add_f32_e32 v150, 1.0, v150
; DI unsigned pk_bf16(float a, float b) { f32x2 v = {a, b}; bf2_t r = __builtin_convertvector(v, bf2_t); return __builtin_bit_cast(unsigned, r); }
; DI float bflo(unsigned u) { return __uint_as_float(u << 16); }
; DI float bfhi(unsigned u) { return __uint_as_float(u & 0xffff0000u); }
; DI float silu_f(float x) { return x * __builtin_amdgcn_rcpf(1.f + __expf(-x)); }
; DI void phase_ret_gate(const Params& p) {
;     ...
;         const float* wn = p.onorm_b + 32 * lane;
; #pragma unroll
;         for (int q = 0; q < 4; ++q) { const u32x4 g = *(const u32x4*)(P1 + (size_t)tok * LDP1 + 4096 + 32 * lane + 8 * q); const unsigned gu[4] = {g.x, g.y, g.z, g.w}; unsigned r[4];
; #pragma unroll
;             for (int i = 0; i < 4; ++i) { const float v0 = o[8 * q + 2 * i] * rstd * wn[8 * q + 2 * i] * silu_f(bflo(gu[i])), v1 = o[8 * q + 2 * i + 1] * rstd * wn[8 * q + 2 * i + 1] * silu_f(bfhi(gu[i])); r[i] = pk_bf16(v0, v1); }
;             *(u32x4*)(og + (size_t)tok * 2048 + 32 * lane + 8 * q) = (u32x4){r[0], r[1], r[2], r[3]}; }
	v_add_f32_e32 v151, 1.0, v151
	v_add_f32_e32 v152, 1.0, v152
	v_add_f32_e32 v153, 1.0, v153
	v_add_f32_e32 v154, 1.0, v154
	v_add_f32_e32 v155, 1.0, v155
	v_rcp_f32_e32 v148, v148
	v_rcp_f32_e32 v149, v149
	v_rcp_f32_e32 v150, v150
	v_rcp_f32_e32 v151, v151
	v_rcp_f32_e32 v152, v152
	v_rcp_f32_e32 v153, v153
	v_rcp_f32_e32 v154, v154
	v_rcp_f32_e32 v155, v155
	v_mul_f32_e32 v222, v148, v222
	v_mul_f32_e32 v223, v149, v223
	v_mul_f32_e32 v224, v150, v224
	v_mul_f32_e32 v225, v151, v225
	v_mul_f32_e32 v226, v152, v226
	v_mul_f32_e32 v227, v153, v227
	v_mul_f32_e32 v228, v154, v228
	v_mul_f32_e32 v229, v155, v229
	s_lshl_b32 s9, s8, 12
	s_add_u32 s20, s16, s9
	s_addc_u32 s21, s17, 0
	v_mul_f32_e32 v112, v144, v112
	v_mul_f32_e32 v113, v144, v113
	v_mul_f32_e32 v114, v144, v114
	v_mul_f32_e32 v115, v144, v115
	v_mul_f32_e32 v116, v144, v116
	v_mul_f32_e32 v117, v144, v117
	v_mul_f32_e32 v118, v144, v118
	v_mul_f32_e32 v119, v144, v119
	v_mul_f32_e32 v112, v16, v112
	v_mul_f32_e32 v113, v17, v113
	v_mul_f32_e32 v114, v18, v114
	v_mul_f32_e32 v115, v19, v115
	v_mul_f32_e32 v116, v20, v116
	v_mul_f32_e32 v117, v21, v117
	v_mul_f32_e32 v118, v22, v118
	v_mul_f32_e32 v119, v23, v119
	v_mul_f32_e32 v112, v198, v112
	v_mul_f32_e32 v113, v199, v113
	v_mul_f32_e32 v114, v200, v114
	v_mul_f32_e32 v115, v201, v115
	v_mul_f32_e32 v116, v202, v116
	v_mul_f32_e32 v117, v203, v117
	v_mul_f32_e32 v118, v204, v118
	v_mul_f32_e32 v119, v205, v119
	v_cvt_pk_bf16_f32 v148, v112, v113
	v_cvt_pk_bf16_f32 v149, v114, v115
	v_cvt_pk_bf16_f32 v150, v116, v117
	v_cvt_pk_bf16_f32 v151, v118, v119
	s_nop 0
	global_store_dwordx4 v2, v[148:151], s[20:21]
	s_nop 1
	v_mul_f32_e32 v120, v145, v120
	v_mul_f32_e32 v121, v145, v121
	v_mul_f32_e32 v122, v145, v122
	v_mul_f32_e32 v123, v145, v123
	v_mul_f32_e32 v124, v145, v124
	v_mul_f32_e32 v125, v145, v125
	v_mul_f32_e32 v126, v145, v126
	v_mul_f32_e32 v127, v145, v127
	v_mul_f32_e32 v120, v24, v120
	v_mul_f32_e32 v121, v25, v121
	v_mul_f32_e32 v122, v26, v122
	v_mul_f32_e32 v123, v27, v123
	v_mul_f32_e32 v124, v28, v124
	v_mul_f32_e32 v125, v29, v125
	v_mul_f32_e32 v126, v30, v126
	v_mul_f32_e32 v127, v31, v127
	v_mul_f32_e32 v120, v206, v120
	v_mul_f32_e32 v121, v207, v121
	v_mul_f32_e32 v122, v208, v122
	v_mul_f32_e32 v123, v209, v123
	v_mul_f32_e32 v124, v210, v124
	v_mul_f32_e32 v125, v211, v125
	v_mul_f32_e32 v126, v212, v126
	v_mul_f32_e32 v127, v213, v127
	v_cvt_pk_bf16_f32 v148, v120, v121
	v_cvt_pk_bf16_f32 v149, v122, v123
	v_cvt_pk_bf16_f32 v150, v124, v125
	v_cvt_pk_bf16_f32 v151, v126, v127
	s_nop 0
	global_store_dwordx4 v2, v[148:151], s[20:21] offset:1024
	s_nop 1
	v_mul_f32_e32 v128, v146, v128
	v_mul_f32_e32 v129, v146, v129
	v_mul_f32_e32 v130, v146, v130
	v_mul_f32_e32 v131, v146, v131
	v_mul_f32_e32 v132, v146, v132
	v_mul_f32_e32 v133, v146, v133
	v_mul_f32_e32 v134, v146, v134
	v_mul_f32_e32 v135, v146, v135
	v_mul_f32_e32 v128, v32, v128
	v_mul_f32_e32 v129, v33, v129
	v_mul_f32_e32 v130, v34, v130
	v_mul_f32_e32 v131, v35, v131
	v_mul_f32_e32 v132, v36, v132
	v_mul_f32_e32 v133, v37, v133
	v_mul_f32_e32 v134, v38, v134
	v_mul_f32_e32 v135, v39, v135
	v_mul_f32_e32 v128, v214, v128
	v_mul_f32_e32 v129, v215, v129
	v_mul_f32_e32 v130, v216, v130
	v_mul_f32_e32 v131, v217, v131
	v_mul_f32_e32 v132, v218, v132
	v_mul_f32_e32 v133, v219, v133
	v_mul_f32_e32 v134, v220, v134
	v_mul_f32_e32 v135, v221, v135
	v_cvt_pk_bf16_f32 v148, v128, v129
	v_cvt_pk_bf16_f32 v149, v130, v131
	v_cvt_pk_bf16_f32 v150, v132, v133
	v_cvt_pk_bf16_f32 v151, v134, v135
	s_nop 0
	global_store_dwordx4 v2, v[148:151], s[20:21] offset:2048
	s_nop 1
	v_mul_f32_e32 v136, v147, v136
	v_mul_f32_e32 v137, v147, v137
	v_mul_f32_e32 v138, v147, v138
	v_mul_f32_e32 v139, v147, v139
	v_mul_f32_e32 v140, v147, v140
	v_mul_f32_e32 v141, v147, v141
	v_mul_f32_e32 v142, v147, v142
	v_mul_f32_e32 v143, v147, v143
	v_mul_f32_e32 v136, v40, v136
	v_mul_f32_e32 v137, v41, v137
	v_mul_f32_e32 v138, v42, v138
	v_mul_f32_e32 v139, v43, v139
	v_mul_f32_e32 v140, v44, v140
	v_mul_f32_e32 v141, v45, v141
	v_mul_f32_e32 v142, v46, v142
	v_mul_f32_e32 v143, v47, v143
	v_mul_f32_e32 v136, v222, v136
	v_mul_f32_e32 v137, v223, v137
	v_mul_f32_e32 v138, v224, v138
	v_mul_f32_e32 v139, v225, v139
	v_mul_f32_e32 v140, v226, v140
	v_mul_f32_e32 v141, v227, v141
	v_mul_f32_e32 v142, v228, v142
	v_mul_f32_e32 v143, v229, v143
	v_cvt_pk_bf16_f32 v148, v136, v137
	v_cvt_pk_bf16_f32 v149, v138, v139
	v_cvt_pk_bf16_f32 v150, v140, v141
	v_cvt_pk_bf16_f32 v151, v142, v143
	s_nop 0
	global_store_dwordx4 v2, v[148:151], s[20:21] offset:3072
	s_nop 1
	s_mov_b32 s8, s22
	s_cmp_lt_u32 s8, 0x4400
	s_cbranch_scc1 .Lg10_a
